# P0: waves 4-7 do the rmsnorm rows first and the weight-transpose items second (waves 0-3 unchanged) so the latency-bound items overlap with bandwidth-bound streaming
# speedup vs baseline: 1.0062x; 1.0062x over previous
.LBB0_5:
	s_or_b64 exec, exec, s[0:1]
	s_add_u32 s82, s76, 0x200000
	s_addc_u32 s83, s77, 0
	s_add_u32 s0, s76, 0xf00000
	s_addc_u32 s1, s77, 0
	s_add_u32 s58, s76, 0x1100000
	s_addc_u32 s59, s77, 0
	s_add_u32 s4, s76, 0x1300000
	s_addc_u32 s5, s77, 0
	v_writelane_b32 v254, s4, 6
	s_mov_b32 s33, 1
	s_nop 0
	v_writelane_b32 v254, s5, 7
	s_add_u32 s4, s76, 0x1e00000
	s_addc_u32 s5, s77, 0
	v_writelane_b32 v254, s4, 8
	s_nop 1
	v_writelane_b32 v254, s5, 9
	s_add_u32 s4, s76, 0x2400000
	s_addc_u32 s5, s77, 0
	v_writelane_b32 v254, s4, 10
	s_cmp_lt_i32 s78, 1
	s_nop 0
	v_writelane_b32 v254, s5, 11
	s_cselect_b64 s[4:5], -1, 0
	s_cmp_gt_i32 s79, 0
	s_cselect_b64 s[6:7], -1, 0
	s_and_b64 s[4:5], s[4:5], s[6:7]
	s_andn2_b64 vcc, exec, s[4:5]
	s_cbranch_vccnz .LBB0_139
	s_mov_b32 s98, 0
.Lp0_redo:
	v_mov_b32_e32 v7, v214
	s_mov_b32 s34, s73
	v_readfirstlane_b32 s4, v7
	s_mov_b32 s35, s69
	s_ashr_i32 s7, s4, 6
	s_lshl_b32 s31, s35, 3
	v_and_b32_e32 v23, 63, v7
	s_lshl_b32 s6, s34, 3
	s_add_i32 s30, s31, s7
	s_cmpk_gt_i32 s30, 0x217f
	v_and_b32_e32 v44, 31, v7
	v_lshlrev_b32_e32 v2, 3, v23
	s_cbranch_scc1 .LBB0_62
	s_cmp_lg_u32 s98, 0
	s_cbranch_scc1 .Lp0_items
	s_bitcmp1_b32 s7, 2
	s_cbranch_scc0 .Lp0_items
	s_mov_b32 s98, 1
	s_branch .LBB0_62
.Lp0_items:
	v_readlane_b32 s26, v254, 0
	v_and_b32_e32 v1, 56, v2
	v_readlane_b32 s8, v254, 8
	v_readlane_b32 s27, v254, 1
	v_lshlrev_b32_e32 v8, 1, v1
	v_mov_b32_e32 v9, 0
	v_readlane_b32 s9, v254, 9
	s_lshl_b32 s16, s7, 14
	v_lshrrev_b32_e32 v45, 3, v23
	v_lshl_add_u64 v[10:11], s[8:9], 0, v[8:9]
	s_load_dwordx4 s[8:11], s[26:27], 0x50
	s_load_dwordx2 s[20:21], s[26:27], 0x40
	s_add_i32 s4, s16, 0
	s_load_dwordx2 s[18:19], s[26:27], 0x70
	v_lshlrev_b32_e32 v3, 2, v44
	v_mul_u32_u24_e32 v5, 0x84, v1
	v_lshlrev_b32_e32 v1, 2, v45
	s_load_dwordx2 s[24:25], s[26:27], 0x10
	s_load_dwordx4 s[12:15], s[26:27], 0x30
	v_lshrrev_b32_e32 v4, 5, v23
	v_add_u32_e32 v6, s4, v3
	v_add3_u32 v46, s4, v5, v1
	v_readlane_b32 s4, v254, 6
	v_readlane_b32 s5, v254, 7
	v_mul_u32_u24_e32 v5, 0x84, v4
	s_waitcnt lgkmcnt(0)
	s_cmp_lg_u64 s[8:9], 0
	v_lshl_add_u64 v[12:13], s[4:5], 0, v[8:9]
	v_lshl_add_u64 v[16:17], s[76:77], 0, v[8:9]
	s_mov_b64 s[4:5], 0xf00400
	v_or_b32_e32 v5, s16, v5
	s_mov_b32 s17, 0
	s_movk_i32 s36, 0x84
	v_or_b32_e32 v47, 8, v45
	v_or_b32_e32 v48, 16, v45
	v_or_b32_e32 v49, 24, v45
	s_cselect_b64 s[22:23], -1, 0
	v_lshl_add_u64 v[14:15], s[58:59], 0, v[8:9]
	v_lshl_add_u64 v[16:17], v[16:17], 0, s[4:5]
	v_lshl_add_u64 v[18:19], s[0:1], 0, v[8:9]
	v_lshl_add_u64 v[20:21], s[82:83], 0, v[8:9]
	v_mov_b32_e32 v1, v4
	v_add3_u32 v50, v5, v3, 0
	v_or_b32_e32 v51, 14, v4
	v_lshlrev_b32_e32 v22, 2, v4
	v_mov_b32_e32 v3, v9
	v_or_b32_e32 v52, 12, v4
	v_or_b32_e32 v53, 10, v4
	v_or_b32_e32 v54, 8, v4
	v_or_b32_e32 v55, 6, v4
	v_or_b32_e32 v56, 4, v4
	v_or_b32_e32 v57, 2, v4
	s_movk_i32 s37, 0x5800
	s_movk_i32 s38, 0x3ff
	s_movk_i32 s39, 0x6800
	s_mov_b32 s40, s30
	s_branch .LBB0_9

.Lp0_items_done:
	s_cmp_eq_u32 s98, 2
	s_cbranch_scc1 .LBB0_71

.LBB0_71:
	s_cmp_eq_u32 s98, 1
	s_cbranch_scc0 .Lp0_done
	s_mov_b32 s98, 2
	s_branch .Lp0_redo
